# phase 5 conv rows hand-written: 8 rows per wave with all 40 loads in flight, counted waits, one joint butterfly for the 8 row sums
# speedup vs baseline: 1.0177x; 1.0085x over previous
; template <int NR>
; __device__ __forceinline__ void conv_rows(const Args& a, int r0, int rstride, int lane) {
;     unsigned char* ws = a.ws; const int c0 = 8 * lane;
;     const bf16* BCp = (const bf16*)(ws + WS_BC); const bf16* CUp = (const bf16*)(ws + WS_CU);
;     v4u bq[NR], u0[NR], u1[NR], u2[NR];
; #pragma unroll
;     for (int i = 0; i < NR; ++i) { const int row = r0 + i * rstride, t = row & (SEQ - 1);
;         bq[i] = *(const v4u*)(BCp + (size_t)row * 512 + c0); u0[i] = *(const v4u*)(CUp + (size_t)row * 512 + c0);
;         u1[i] = (v4u){0, 0, 0, 0}; u2[i] = (v4u){0, 0, 0, 0};
;         if (t >= 1) u1[i] = *(const v4u*)(CUp + (size_t)(row - 1) * 512 + c0);
;         if (t >= 2) u2[i] = *(const v4u*)(CUp + (size_t)(row - 2) * 512 + c0); }
;     const float* cw = a.in[I_CONVW] + c0; const float* gn = a.in[I_CONVN] + c0;
;     const f32x4 w0a = *(const f32x4*)(cw), w0b = *(const f32x4*)(cw + 4), w1a = *(const f32x4*)(cw + 512), w1b = *(const f32x4*)(cw + 516), w2a = *(const f32x4*)(cw + 1024), w2b = *(const f32x4*)(cw + 1028);
;     const f32x4 ga = *(const f32x4*)(gn), gb = *(const f32x4*)(gn + 4);
; #pragma unroll
;     for (int i = 0; i < NR; ++i) { const int row = r0 + i * rstride; float y[8]; float s = 0.f;
; #pragma unroll
;         for (int j = 0; j < 8; ++j) { const int sh = (j & 1) * 16; const unsigned ub = bq[i][j >> 1], x0 = u0[i][j >> 1], x1 = u1[i][j >> 1], x2 = u2[i][j >> 1];
;             const float B = __uint_as_float(((ub >> sh) & 0xffffu) << 16), c_0 = __uint_as_float(((x0 >> sh) & 0xffffu) << 16), c_1 = __uint_as_float(((x1 >> sh) & 0xffffu) << 16), c_2 = __uint_as_float(((x2 >> sh) & 0xffffu) << 16);
;             const float k0 = j < 4 ? w0a[j & 3] : w0b[j & 3], k1 = j < 4 ? w1a[j & 3] : w1b[j & 3], k2 = j < 4 ? w2a[j & 3] : w2b[j & 3];
;             y[j] = B * (k0 * c_2 + k1 * c_1 + k2 * c_0); s += y[j] * y[j]; }
.Lp5_sync:
	s_waitcnt vmcnt(0) lgkmcnt(0)
	s_barrier
	s_cmpk_lg_i32 s3, 0x100
	s_cbranch_scc1 .Lc8_generic
	s_load_dwordx4 s[16:19], s[0:1], 0xa8
	s_load_dwordx4 s[12:15], s[0:1], 0x40
	s_load_dwordx2 s[8:9], s[0:1], 0x50
	v_lshlrev_b32_e32 v0, 4, v208
	v_lshlrev_b32_e32 v1, 5, v208
	s_waitcnt lgkmcnt(0)
	global_load_dwordx4 v[2:5], v1, s[14:15]
	global_load_dwordx4 v[6:9], v1, s[14:15] offset:16
	global_load_dwordx4 v[10:13], v1, s[14:15] offset:2048
	global_load_dwordx4 v[14:17], v1, s[14:15] offset:2064
	s_add_u32 s4, s14, 0x1000
	s_addc_u32 s5, s15, 0
	global_load_dwordx4 v[18:21], v1, s[4:5]
	global_load_dwordx4 v[22:25], v1, s[4:5] offset:16
	global_load_dwordx4 v[26:29], v1, s[8:9]
	global_load_dwordx4 v[30:33], v1, s[8:9] offset:16
	s_add_u32 s20, s18, 0xa000000
	s_addc_u32 s21, s19, 0
	s_add_u32 s22, s18, 0xb000000
	s_addc_u32 s23, s19, 0
	s_add_i32 s10, s24, 0x0
	s_lshl_b32 s11, s10, 10
	s_add_u32 s4, s20, s11
	s_addc_u32 s5, s21, 0
	s_add_u32 s6, s22, s11
	s_addc_u32 s7, s23, 0
	global_load_dwordx4 v[40:43], v0, s[4:5]
	global_load_dwordx4 v[44:47], v0, s[6:7]
	global_load_dwordx4 v[48:51], v0, s[6:7] offset:-1024
	global_load_dwordx4 v[52:55], v0, s[6:7] offset:-2048
	s_add_i32 s10, s24, 0x800
	s_lshl_b32 s11, s10, 10
	s_add_u32 s4, s20, s11
	s_addc_u32 s5, s21, 0
	s_add_u32 s6, s22, s11
	s_addc_u32 s7, s23, 0
	global_load_dwordx4 v[56:59], v0, s[4:5]
	global_load_dwordx4 v[60:63], v0, s[6:7]
	global_load_dwordx4 v[64:67], v0, s[6:7] offset:-1024
	global_load_dwordx4 v[68:71], v0, s[6:7] offset:-2048
	s_add_i32 s10, s24, 0x1000
	s_lshl_b32 s11, s10, 10
	s_add_u32 s4, s20, s11
	s_addc_u32 s5, s21, 0
	s_add_u32 s6, s22, s11
	s_addc_u32 s7, s23, 0
	global_load_dwordx4 v[72:75], v0, s[4:5]
	global_load_dwordx4 v[76:79], v0, s[6:7]
	global_load_dwordx4 v[80:83], v0, s[6:7] offset:-1024
	global_load_dwordx4 v[84:87], v0, s[6:7] offset:-2048
	s_add_i32 s10, s24, 0x1800
	s_lshl_b32 s11, s10, 10
	s_add_u32 s4, s20, s11
	s_addc_u32 s5, s21, 0
	s_add_u32 s6, s22, s11
	s_addc_u32 s7, s23, 0
	global_load_dwordx4 v[88:91], v0, s[4:5]
	global_load_dwordx4 v[92:95], v0, s[6:7]
	global_load_dwordx4 v[96:99], v0, s[6:7] offset:-1024
	global_load_dwordx4 v[100:103], v0, s[6:7] offset:-2048
	s_add_i32 s10, s24, 0x2000
	s_lshl_b32 s11, s10, 10
	s_add_u32 s4, s20, s11
	s_addc_u32 s5, s21, 0
	s_add_u32 s6, s22, s11
	s_addc_u32 s7, s23, 0
	global_load_dwordx4 v[104:107], v0, s[4:5]
	global_load_dwordx4 v[108:111], v0, s[6:7]
	global_load_dwordx4 v[112:115], v0, s[6:7] offset:-1024
	global_load_dwordx4 v[116:119], v0, s[6:7] offset:-2048
	s_add_i32 s10, s24, 0x2800
	s_lshl_b32 s11, s10, 10
	s_add_u32 s4, s20, s11
	s_addc_u32 s5, s21, 0
	s_add_u32 s6, s22, s11
	s_addc_u32 s7, s23, 0
	global_load_dwordx4 v[120:123], v0, s[4:5]
	global_load_dwordx4 v[124:127], v0, s[6:7]
	global_load_dwordx4 v[128:131], v0, s[6:7] offset:-1024
	global_load_dwordx4 v[132:135], v0, s[6:7] offset:-2048
	s_add_i32 s10, s24, 0x3000
	s_lshl_b32 s11, s10, 10
	s_add_u32 s4, s20, s11
	s_addc_u32 s5, s21, 0
	s_add_u32 s6, s22, s11
	s_addc_u32 s7, s23, 0
	global_load_dwordx4 v[136:139], v0, s[4:5]
	global_load_dwordx4 v[140:143], v0, s[6:7]
	global_load_dwordx4 v[144:147], v0, s[6:7] offset:-1024
	global_load_dwordx4 v[148:151], v0, s[6:7] offset:-2048
	s_add_i32 s10, s24, 0x3800
	s_lshl_b32 s11, s10, 10
	s_add_u32 s4, s20, s11
	s_addc_u32 s5, s21, 0
	s_add_u32 s6, s22, s11
	s_addc_u32 s7, s23, 0
	global_load_dwordx4 v[152:155], v0, s[4:5]
	global_load_dwordx4 v[156:159], v0, s[6:7]
	global_load_dwordx4 v[160:163], v0, s[6:7] offset:-1024
	global_load_dwordx4 v[164:167], v0, s[6:7] offset:-2048
	s_waitcnt vmcnt(28)
	s_add_i32 s10, s24, 0x0
	s_and_b32 s11, s10, 0xfff
	s_cmp_lg_u32 s11, 0
	s_cbranch_scc1 .Lc8_k1_0
	v_mov_b32_e32 v48, 0
	v_mov_b32_e32 v49, 0
	v_mov_b32_e32 v50, 0
	v_mov_b32_e32 v51, 0
.Lc8_k1_0:
	s_cmp_gt_u32 s11, 1
	s_cbranch_scc1 .Lc8_k2_0
	v_mov_b32_e32 v52, 0
	v_mov_b32_e32 v53, 0
	v_mov_b32_e32 v54, 0
	v_mov_b32_e32 v55, 0
.Lc8_k2_0:
	v_lshlrev_b32_e32 v234, 16, v52
	v_and_b32_e32 v235, 0xffff0000, v52
	v_lshlrev_b32_e32 v236, 16, v48
	v_and_b32_e32 v237, 0xffff0000, v48
	v_lshlrev_b32_e32 v238, 16, v44
	v_and_b32_e32 v239, 0xffff0000, v44
	v_lshlrev_b32_e32 v240, 16, v40
	v_and_b32_e32 v241, 0xffff0000, v40
	v_pk_mul_f32 v[242:243], v[2:3], v[234:235]
	v_pk_fma_f32 v[242:243], v[10:11], v[236:237], v[242:243]
	v_pk_fma_f32 v[242:243], v[18:19], v[238:239], v[242:243]
	v_pk_mul_f32 v[168:169], v[242:243], v[240:241]
	v_pk_mul_f32 v[244:245], v[168:169], v[168:169]
	v_lshlrev_b32_e32 v234, 16, v53
	v_and_b32_e32 v235, 0xffff0000, v53
	v_lshlrev_b32_e32 v236, 16, v49
	v_and_b32_e32 v237, 0xffff0000, v49
	v_lshlrev_b32_e32 v238, 16, v45
	v_and_b32_e32 v239, 0xffff0000, v45
	v_lshlrev_b32_e32 v240, 16, v41
	v_and_b32_e32 v241, 0xffff0000, v41
	v_pk_mul_f32 v[242:243], v[4:5], v[234:235]
	v_pk_fma_f32 v[242:243], v[12:13], v[236:237], v[242:243]
	v_pk_fma_f32 v[242:243], v[20:21], v[238:239], v[242:243]
	v_pk_mul_f32 v[170:171], v[242:243], v[240:241]
	v_pk_fma_f32 v[244:245], v[170:171], v[170:171], v[244:245]
	v_lshlrev_b32_e32 v234, 16, v54
	v_and_b32_e32 v235, 0xffff0000, v54
	v_lshlrev_b32_e32 v236, 16, v50
	v_and_b32_e32 v237, 0xffff0000, v50
	v_lshlrev_b32_e32 v238, 16, v46
	v_and_b32_e32 v239, 0xffff0000, v46
	v_lshlrev_b32_e32 v240, 16, v42
	v_and_b32_e32 v241, 0xffff0000, v42
	v_pk_mul_f32 v[242:243], v[6:7], v[234:235]
	v_pk_fma_f32 v[242:243], v[14:15], v[236:237], v[242:243]
	v_pk_fma_f32 v[242:243], v[22:23], v[238:239], v[242:243]
	v_pk_mul_f32 v[172:173], v[242:243], v[240:241]
	v_pk_fma_f32 v[244:245], v[172:173], v[172:173], v[244:245]
	v_lshlrev_b32_e32 v234, 16, v55
	v_and_b32_e32 v235, 0xffff0000, v55
	v_lshlrev_b32_e32 v236, 16, v51
	v_and_b32_e32 v237, 0xffff0000, v51
	v_lshlrev_b32_e32 v238, 16, v47
	v_and_b32_e32 v239, 0xffff0000, v47
	v_lshlrev_b32_e32 v240, 16, v43
	v_and_b32_e32 v241, 0xffff0000, v43
	v_pk_mul_f32 v[242:243], v[8:9], v[234:235]
	v_pk_fma_f32 v[242:243], v[16:17], v[236:237], v[242:243]
	v_pk_fma_f32 v[242:243], v[24:25], v[238:239], v[242:243]
	v_pk_mul_f32 v[174:175], v[242:243], v[240:241]
	v_pk_fma_f32 v[244:245], v[174:175], v[174:175], v[244:245]
	v_add_f32_e32 v40, v244, v245
	s_waitcnt vmcnt(24)
	s_add_i32 s10, s24, 0x800
	s_and_b32 s11, s10, 0xfff
	s_cmp_lg_u32 s11, 0
	s_cbranch_scc1 .Lc8_k1_1
	v_mov_b32_e32 v64, 0
	v_mov_b32_e32 v65, 0
	v_mov_b32_e32 v66, 0
	v_mov_b32_e32 v67, 0
; template <int NR>
; __device__ __forceinline__ void conv_rows(const Args& a, int r0, int rstride, int lane) {
;     ...
;     for (int i = 0; i < NR; ++i) { const int row = r0 + i * rstride; float y[8]; float s = 0.f;
; #pragma unroll
;         for (int j = 0; j < 8; ++j) { const int sh = (j & 1) * 16; const unsigned ub = bq[i][j >> 1], x0 = u0[i][j >> 1], x1 = u1[i][j >> 1], x2 = u2[i][j >> 1];
;             const float B = __uint_as_float(((ub >> sh) & 0xffffu) << 16), c_0 = __uint_as_float(((x0 >> sh) & 0xffffu) << 16), c_1 = __uint_as_float(((x1 >> sh) & 0xffffu) << 16), c_2 = __uint_as_float(((x2 >> sh) & 0xffffu) << 16);
;             const float k0 = j < 4 ? w0a[j & 3] : w0b[j & 3], k1 = j < 4 ? w1a[j & 3] : w1b[j & 3], k2 = j < 4 ? w2a[j & 3] : w2b[j & 3];
;             y[j] = B * (k0 * c_2 + k1 * c_1 + k2 * c_0); s += y[j] * y[j]; }
.Lc8_k1_1:
	s_cmp_gt_u32 s11, 1
	s_cbranch_scc1 .Lc8_k2_1
	v_mov_b32_e32 v68, 0
	v_mov_b32_e32 v69, 0
	v_mov_b32_e32 v70, 0
	v_mov_b32_e32 v71, 0
.Lc8_k2_1:
	v_lshlrev_b32_e32 v234, 16, v68
	v_and_b32_e32 v235, 0xffff0000, v68
	v_lshlrev_b32_e32 v236, 16, v64
	v_and_b32_e32 v237, 0xffff0000, v64
	v_lshlrev_b32_e32 v238, 16, v60
	v_and_b32_e32 v239, 0xffff0000, v60
	v_lshlrev_b32_e32 v240, 16, v56
	v_and_b32_e32 v241, 0xffff0000, v56
	v_pk_mul_f32 v[242:243], v[2:3], v[234:235]
	v_pk_fma_f32 v[242:243], v[10:11], v[236:237], v[242:243]
	v_pk_fma_f32 v[242:243], v[18:19], v[238:239], v[242:243]
	v_pk_mul_f32 v[176:177], v[242:243], v[240:241]
	v_pk_mul_f32 v[244:245], v[176:177], v[176:177]
	v_lshlrev_b32_e32 v234, 16, v69
	v_and_b32_e32 v235, 0xffff0000, v69
	v_lshlrev_b32_e32 v236, 16, v65
	v_and_b32_e32 v237, 0xffff0000, v65
	v_lshlrev_b32_e32 v238, 16, v61
	v_and_b32_e32 v239, 0xffff0000, v61
	v_lshlrev_b32_e32 v240, 16, v57
	v_and_b32_e32 v241, 0xffff0000, v57
	v_pk_mul_f32 v[242:243], v[4:5], v[234:235]
	v_pk_fma_f32 v[242:243], v[12:13], v[236:237], v[242:243]
	v_pk_fma_f32 v[242:243], v[20:21], v[238:239], v[242:243]
	v_pk_mul_f32 v[178:179], v[242:243], v[240:241]
	v_pk_fma_f32 v[244:245], v[178:179], v[178:179], v[244:245]
	v_lshlrev_b32_e32 v234, 16, v70
	v_and_b32_e32 v235, 0xffff0000, v70
	v_lshlrev_b32_e32 v236, 16, v66
	v_and_b32_e32 v237, 0xffff0000, v66
	v_lshlrev_b32_e32 v238, 16, v62
	v_and_b32_e32 v239, 0xffff0000, v62
	v_lshlrev_b32_e32 v240, 16, v58
	v_and_b32_e32 v241, 0xffff0000, v58
	v_pk_mul_f32 v[242:243], v[6:7], v[234:235]
	v_pk_fma_f32 v[242:243], v[14:15], v[236:237], v[242:243]
	v_pk_fma_f32 v[242:243], v[22:23], v[238:239], v[242:243]
	v_pk_mul_f32 v[180:181], v[242:243], v[240:241]
	v_pk_fma_f32 v[244:245], v[180:181], v[180:181], v[244:245]
	v_lshlrev_b32_e32 v234, 16, v71
	v_and_b32_e32 v235, 0xffff0000, v71
	v_lshlrev_b32_e32 v236, 16, v67
	v_and_b32_e32 v237, 0xffff0000, v67
	v_lshlrev_b32_e32 v238, 16, v63
	v_and_b32_e32 v239, 0xffff0000, v63
	v_lshlrev_b32_e32 v240, 16, v59
	v_and_b32_e32 v241, 0xffff0000, v59
	v_pk_mul_f32 v[242:243], v[8:9], v[234:235]
	v_pk_fma_f32 v[242:243], v[16:17], v[236:237], v[242:243]
	v_pk_fma_f32 v[242:243], v[24:25], v[238:239], v[242:243]
	v_pk_mul_f32 v[182:183], v[242:243], v[240:241]
	v_pk_fma_f32 v[244:245], v[182:183], v[182:183], v[244:245]
	v_add_f32_e32 v42, v244, v245
	s_waitcnt vmcnt(20)
	s_add_i32 s10, s24, 0x1000
	s_and_b32 s11, s10, 0xfff
	s_cmp_lg_u32 s11, 0
	s_cbranch_scc1 .Lc8_k1_2
	v_mov_b32_e32 v80, 0
	v_mov_b32_e32 v81, 0
	v_mov_b32_e32 v82, 0
	v_mov_b32_e32 v83, 0
.Lc8_k1_2:
	s_cmp_gt_u32 s11, 1
	s_cbranch_scc1 .Lc8_k2_2
	v_mov_b32_e32 v84, 0
	v_mov_b32_e32 v85, 0
	v_mov_b32_e32 v86, 0
	v_mov_b32_e32 v87, 0
.Lc8_k2_2:
	v_lshlrev_b32_e32 v234, 16, v84
	v_and_b32_e32 v235, 0xffff0000, v84
	v_lshlrev_b32_e32 v236, 16, v80
	v_and_b32_e32 v237, 0xffff0000, v80
	v_lshlrev_b32_e32 v238, 16, v76
	v_and_b32_e32 v239, 0xffff0000, v76
	v_lshlrev_b32_e32 v240, 16, v72
	v_and_b32_e32 v241, 0xffff0000, v72
	v_pk_mul_f32 v[242:243], v[2:3], v[234:235]
	v_pk_fma_f32 v[242:243], v[10:11], v[236:237], v[242:243]
	v_pk_fma_f32 v[242:243], v[18:19], v[238:239], v[242:243]
	v_pk_mul_f32 v[184:185], v[242:243], v[240:241]
	v_pk_mul_f32 v[244:245], v[184:185], v[184:185]
	v_lshlrev_b32_e32 v234, 16, v85
	v_and_b32_e32 v235, 0xffff0000, v85
	v_lshlrev_b32_e32 v236, 16, v81
	v_and_b32_e32 v237, 0xffff0000, v81
	v_lshlrev_b32_e32 v238, 16, v77
	v_and_b32_e32 v239, 0xffff0000, v77
	v_lshlrev_b32_e32 v240, 16, v73
	v_and_b32_e32 v241, 0xffff0000, v73
	v_pk_mul_f32 v[242:243], v[4:5], v[234:235]
	v_pk_fma_f32 v[242:243], v[12:13], v[236:237], v[242:243]
	v_pk_fma_f32 v[242:243], v[20:21], v[238:239], v[242:243]
	v_pk_mul_f32 v[186:187], v[242:243], v[240:241]
	v_pk_fma_f32 v[244:245], v[186:187], v[186:187], v[244:245]
	v_lshlrev_b32_e32 v234, 16, v86
	v_and_b32_e32 v235, 0xffff0000, v86
	v_lshlrev_b32_e32 v236, 16, v82
	v_and_b32_e32 v237, 0xffff0000, v82
	v_lshlrev_b32_e32 v238, 16, v78
	v_and_b32_e32 v239, 0xffff0000, v78
	v_lshlrev_b32_e32 v240, 16, v74
	v_and_b32_e32 v241, 0xffff0000, v74
	v_pk_mul_f32 v[242:243], v[6:7], v[234:235]
	v_pk_fma_f32 v[242:243], v[14:15], v[236:237], v[242:243]
	v_pk_fma_f32 v[242:243], v[22:23], v[238:239], v[242:243]
	v_pk_mul_f32 v[188:189], v[242:243], v[240:241]
	v_pk_fma_f32 v[244:245], v[188:189], v[188:189], v[244:245]
	v_lshlrev_b32_e32 v234, 16, v87
	v_and_b32_e32 v235, 0xffff0000, v87
	v_lshlrev_b32_e32 v236, 16, v83
	v_and_b32_e32 v237, 0xffff0000, v83
	v_lshlrev_b32_e32 v238, 16, v79
	v_and_b32_e32 v239, 0xffff0000, v79
	v_lshlrev_b32_e32 v240, 16, v75
	v_and_b32_e32 v241, 0xffff0000, v75
	v_pk_mul_f32 v[242:243], v[8:9], v[234:235]
	v_pk_fma_f32 v[242:243], v[16:17], v[236:237], v[242:243]
	v_pk_fma_f32 v[242:243], v[24:25], v[238:239], v[242:243]
	v_pk_mul_f32 v[190:191], v[242:243], v[240:241]
	v_pk_fma_f32 v[244:245], v[190:191], v[190:191], v[244:245]
	v_add_f32_e32 v44, v244, v245
	s_waitcnt vmcnt(16)
	s_add_i32 s10, s24, 0x1800
	s_and_b32 s11, s10, 0xfff
	s_cmp_lg_u32 s11, 0
	s_cbranch_scc1 .Lc8_k1_3
	v_mov_b32_e32 v96, 0
	v_mov_b32_e32 v97, 0
	v_mov_b32_e32 v98, 0
	v_mov_b32_e32 v99, 0
.Lc8_k1_3:
	s_cmp_gt_u32 s11, 1
	s_cbranch_scc1 .Lc8_k2_3
	v_mov_b32_e32 v100, 0
	v_mov_b32_e32 v101, 0
	v_mov_b32_e32 v102, 0
	v_mov_b32_e32 v103, 0
; template <int NR>
; __device__ __forceinline__ void conv_rows(const Args& a, int r0, int rstride, int lane) {
;     ...
;     for (int i = 0; i < NR; ++i) { const int row = r0 + i * rstride; float y[8]; float s = 0.f;
; #pragma unroll
;         for (int j = 0; j < 8; ++j) { const int sh = (j & 1) * 16; const unsigned ub = bq[i][j >> 1], x0 = u0[i][j >> 1], x1 = u1[i][j >> 1], x2 = u2[i][j >> 1];
;             const float B = __uint_as_float(((ub >> sh) & 0xffffu) << 16), c_0 = __uint_as_float(((x0 >> sh) & 0xffffu) << 16), c_1 = __uint_as_float(((x1 >> sh) & 0xffffu) << 16), c_2 = __uint_as_float(((x2 >> sh) & 0xffffu) << 16);
;             const float k0 = j < 4 ? w0a[j & 3] : w0b[j & 3], k1 = j < 4 ? w1a[j & 3] : w1b[j & 3], k2 = j < 4 ? w2a[j & 3] : w2b[j & 3];
;             y[j] = B * (k0 * c_2 + k1 * c_1 + k2 * c_0); s += y[j] * y[j]; }
.Lc8_k2_3:
	v_lshlrev_b32_e32 v234, 16, v100
	v_and_b32_e32 v235, 0xffff0000, v100
	v_lshlrev_b32_e32 v236, 16, v96
	v_and_b32_e32 v237, 0xffff0000, v96
	v_lshlrev_b32_e32 v238, 16, v92
	v_and_b32_e32 v239, 0xffff0000, v92
	v_lshlrev_b32_e32 v240, 16, v88
	v_and_b32_e32 v241, 0xffff0000, v88
	v_pk_mul_f32 v[242:243], v[2:3], v[234:235]
	v_pk_fma_f32 v[242:243], v[10:11], v[236:237], v[242:243]
	v_pk_fma_f32 v[242:243], v[18:19], v[238:239], v[242:243]
	v_pk_mul_f32 v[192:193], v[242:243], v[240:241]
	v_pk_mul_f32 v[244:245], v[192:193], v[192:193]
	v_lshlrev_b32_e32 v234, 16, v101
	v_and_b32_e32 v235, 0xffff0000, v101
	v_lshlrev_b32_e32 v236, 16, v97
	v_and_b32_e32 v237, 0xffff0000, v97
	v_lshlrev_b32_e32 v238, 16, v93
	v_and_b32_e32 v239, 0xffff0000, v93
	v_lshlrev_b32_e32 v240, 16, v89
	v_and_b32_e32 v241, 0xffff0000, v89
	v_pk_mul_f32 v[242:243], v[4:5], v[234:235]
	v_pk_fma_f32 v[242:243], v[12:13], v[236:237], v[242:243]
	v_pk_fma_f32 v[242:243], v[20:21], v[238:239], v[242:243]
	v_pk_mul_f32 v[194:195], v[242:243], v[240:241]
	v_pk_fma_f32 v[244:245], v[194:195], v[194:195], v[244:245]
	v_lshlrev_b32_e32 v234, 16, v102
	v_and_b32_e32 v235, 0xffff0000, v102
	v_lshlrev_b32_e32 v236, 16, v98
	v_and_b32_e32 v237, 0xffff0000, v98
	v_lshlrev_b32_e32 v238, 16, v94
	v_and_b32_e32 v239, 0xffff0000, v94
	v_lshlrev_b32_e32 v240, 16, v90
	v_and_b32_e32 v241, 0xffff0000, v90
	v_pk_mul_f32 v[242:243], v[6:7], v[234:235]
	v_pk_fma_f32 v[242:243], v[14:15], v[236:237], v[242:243]
	v_pk_fma_f32 v[242:243], v[22:23], v[238:239], v[242:243]
	v_pk_mul_f32 v[196:197], v[242:243], v[240:241]
	v_pk_fma_f32 v[244:245], v[196:197], v[196:197], v[244:245]
	v_lshlrev_b32_e32 v234, 16, v103
	v_and_b32_e32 v235, 0xffff0000, v103
	v_lshlrev_b32_e32 v236, 16, v99
	v_and_b32_e32 v237, 0xffff0000, v99
	v_lshlrev_b32_e32 v238, 16, v95
	v_and_b32_e32 v239, 0xffff0000, v95
	v_lshlrev_b32_e32 v240, 16, v91
	v_and_b32_e32 v241, 0xffff0000, v91
	v_pk_mul_f32 v[242:243], v[8:9], v[234:235]
	v_pk_fma_f32 v[242:243], v[16:17], v[236:237], v[242:243]
	v_pk_fma_f32 v[242:243], v[24:25], v[238:239], v[242:243]
	v_pk_mul_f32 v[198:199], v[242:243], v[240:241]
	v_pk_fma_f32 v[244:245], v[198:199], v[198:199], v[244:245]
	v_add_f32_e32 v46, v244, v245
	s_waitcnt vmcnt(12)
	s_add_i32 s10, s24, 0x2000
	s_and_b32 s11, s10, 0xfff
	s_cmp_lg_u32 s11, 0
	s_cbranch_scc1 .Lc8_k1_4
	v_mov_b32_e32 v112, 0
	v_mov_b32_e32 v113, 0
	v_mov_b32_e32 v114, 0
	v_mov_b32_e32 v115, 0
.Lc8_k1_4:
	s_cmp_gt_u32 s11, 1
	s_cbranch_scc1 .Lc8_k2_4
	v_mov_b32_e32 v116, 0
	v_mov_b32_e32 v117, 0
	v_mov_b32_e32 v118, 0
	v_mov_b32_e32 v119, 0
.Lc8_k2_4:
	v_lshlrev_b32_e32 v234, 16, v116
	v_and_b32_e32 v235, 0xffff0000, v116
	v_lshlrev_b32_e32 v236, 16, v112
	v_and_b32_e32 v237, 0xffff0000, v112
	v_lshlrev_b32_e32 v238, 16, v108
	v_and_b32_e32 v239, 0xffff0000, v108
	v_lshlrev_b32_e32 v240, 16, v104
	v_and_b32_e32 v241, 0xffff0000, v104
	v_pk_mul_f32 v[242:243], v[2:3], v[234:235]
	v_pk_fma_f32 v[242:243], v[10:11], v[236:237], v[242:243]
	v_pk_fma_f32 v[242:243], v[18:19], v[238:239], v[242:243]
	v_pk_mul_f32 v[200:201], v[242:243], v[240:241]
	v_pk_mul_f32 v[244:245], v[200:201], v[200:201]
	v_lshlrev_b32_e32 v234, 16, v117
	v_and_b32_e32 v235, 0xffff0000, v117
	v_lshlrev_b32_e32 v236, 16, v113
	v_and_b32_e32 v237, 0xffff0000, v113
	v_lshlrev_b32_e32 v238, 16, v109
	v_and_b32_e32 v239, 0xffff0000, v109
	v_lshlrev_b32_e32 v240, 16, v105
	v_and_b32_e32 v241, 0xffff0000, v105
	v_pk_mul_f32 v[242:243], v[4:5], v[234:235]
	v_pk_fma_f32 v[242:243], v[12:13], v[236:237], v[242:243]
	v_pk_fma_f32 v[242:243], v[20:21], v[238:239], v[242:243]
	v_pk_mul_f32 v[202:203], v[242:243], v[240:241]
	v_pk_fma_f32 v[244:245], v[202:203], v[202:203], v[244:245]
	v_lshlrev_b32_e32 v234, 16, v118
	v_and_b32_e32 v235, 0xffff0000, v118
	v_lshlrev_b32_e32 v236, 16, v114
	v_and_b32_e32 v237, 0xffff0000, v114
	v_lshlrev_b32_e32 v238, 16, v110
	v_and_b32_e32 v239, 0xffff0000, v110
	v_lshlrev_b32_e32 v240, 16, v106
	v_and_b32_e32 v241, 0xffff0000, v106
	v_pk_mul_f32 v[242:243], v[6:7], v[234:235]
	v_pk_fma_f32 v[242:243], v[14:15], v[236:237], v[242:243]
	v_pk_fma_f32 v[242:243], v[22:23], v[238:239], v[242:243]
	v_pk_mul_f32 v[204:205], v[242:243], v[240:241]
	v_pk_fma_f32 v[244:245], v[204:205], v[204:205], v[244:245]
	v_lshlrev_b32_e32 v234, 16, v119
	v_and_b32_e32 v235, 0xffff0000, v119
	v_lshlrev_b32_e32 v236, 16, v115
	v_and_b32_e32 v237, 0xffff0000, v115
	v_lshlrev_b32_e32 v238, 16, v111
	v_and_b32_e32 v239, 0xffff0000, v111
	v_lshlrev_b32_e32 v240, 16, v107
	v_and_b32_e32 v241, 0xffff0000, v107
	v_pk_mul_f32 v[242:243], v[8:9], v[234:235]
	v_pk_fma_f32 v[242:243], v[16:17], v[236:237], v[242:243]
	v_pk_fma_f32 v[242:243], v[24:25], v[238:239], v[242:243]
	v_pk_mul_f32 v[206:207], v[242:243], v[240:241]
	v_pk_fma_f32 v[244:245], v[206:207], v[206:207], v[244:245]
	v_add_f32_e32 v48, v244, v245
	s_waitcnt vmcnt(8)
	s_add_i32 s10, s24, 0x2800
	s_and_b32 s11, s10, 0xfff
	s_cmp_lg_u32 s11, 0
	s_cbranch_scc1 .Lc8_k1_5
	v_mov_b32_e32 v128, 0
	v_mov_b32_e32 v129, 0
	v_mov_b32_e32 v130, 0
	v_mov_b32_e32 v131, 0
.Lc8_k1_5:
	s_cmp_gt_u32 s11, 1
	s_cbranch_scc1 .Lc8_k2_5
	v_mov_b32_e32 v132, 0
	v_mov_b32_e32 v133, 0
	v_mov_b32_e32 v134, 0
	v_mov_b32_e32 v135, 0
; template <int NR>
; __device__ __forceinline__ void conv_rows(const Args& a, int r0, int rstride, int lane) {
;     ...
;     for (int i = 0; i < NR; ++i) { const int row = r0 + i * rstride; float y[8]; float s = 0.f;
; #pragma unroll
;         for (int j = 0; j < 8; ++j) { const int sh = (j & 1) * 16; const unsigned ub = bq[i][j >> 1], x0 = u0[i][j >> 1], x1 = u1[i][j >> 1], x2 = u2[i][j >> 1];
;             const float B = __uint_as_float(((ub >> sh) & 0xffffu) << 16), c_0 = __uint_as_float(((x0 >> sh) & 0xffffu) << 16), c_1 = __uint_as_float(((x1 >> sh) & 0xffffu) << 16), c_2 = __uint_as_float(((x2 >> sh) & 0xffffu) << 16);
;             const float k0 = j < 4 ? w0a[j & 3] : w0b[j & 3], k1 = j < 4 ? w1a[j & 3] : w1b[j & 3], k2 = j < 4 ? w2a[j & 3] : w2b[j & 3];
;             y[j] = B * (k0 * c_2 + k1 * c_1 + k2 * c_0); s += y[j] * y[j]; }
.Lc8_k2_5:
	v_lshlrev_b32_e32 v234, 16, v132
	v_and_b32_e32 v235, 0xffff0000, v132
	v_lshlrev_b32_e32 v236, 16, v128
	v_and_b32_e32 v237, 0xffff0000, v128
	v_lshlrev_b32_e32 v238, 16, v124
	v_and_b32_e32 v239, 0xffff0000, v124
	v_lshlrev_b32_e32 v240, 16, v120
	v_and_b32_e32 v241, 0xffff0000, v120
	v_pk_mul_f32 v[242:243], v[2:3], v[234:235]
	v_pk_fma_f32 v[242:243], v[10:11], v[236:237], v[242:243]
	v_pk_fma_f32 v[242:243], v[18:19], v[238:239], v[242:243]
	v_pk_mul_f32 v[210:211], v[242:243], v[240:241]
	v_pk_mul_f32 v[244:245], v[210:211], v[210:211]
	v_lshlrev_b32_e32 v234, 16, v133
	v_and_b32_e32 v235, 0xffff0000, v133
	v_lshlrev_b32_e32 v236, 16, v129
	v_and_b32_e32 v237, 0xffff0000, v129
	v_lshlrev_b32_e32 v238, 16, v125
	v_and_b32_e32 v239, 0xffff0000, v125
	v_lshlrev_b32_e32 v240, 16, v121
	v_and_b32_e32 v241, 0xffff0000, v121
	v_pk_mul_f32 v[242:243], v[4:5], v[234:235]
	v_pk_fma_f32 v[242:243], v[12:13], v[236:237], v[242:243]
	v_pk_fma_f32 v[242:243], v[20:21], v[238:239], v[242:243]
	v_pk_mul_f32 v[212:213], v[242:243], v[240:241]
	v_pk_fma_f32 v[244:245], v[212:213], v[212:213], v[244:245]
	v_lshlrev_b32_e32 v234, 16, v134
	v_and_b32_e32 v235, 0xffff0000, v134
	v_lshlrev_b32_e32 v236, 16, v130
	v_and_b32_e32 v237, 0xffff0000, v130
	v_lshlrev_b32_e32 v238, 16, v126
	v_and_b32_e32 v239, 0xffff0000, v126
	v_lshlrev_b32_e32 v240, 16, v122
	v_and_b32_e32 v241, 0xffff0000, v122
	v_pk_mul_f32 v[242:243], v[6:7], v[234:235]
	v_pk_fma_f32 v[242:243], v[14:15], v[236:237], v[242:243]
	v_pk_fma_f32 v[242:243], v[22:23], v[238:239], v[242:243]
	v_pk_mul_f32 v[214:215], v[242:243], v[240:241]
	v_pk_fma_f32 v[244:245], v[214:215], v[214:215], v[244:245]
	v_lshlrev_b32_e32 v234, 16, v135
	v_and_b32_e32 v235, 0xffff0000, v135
	v_lshlrev_b32_e32 v236, 16, v131
	v_and_b32_e32 v237, 0xffff0000, v131
	v_lshlrev_b32_e32 v238, 16, v127
	v_and_b32_e32 v239, 0xffff0000, v127
	v_lshlrev_b32_e32 v240, 16, v123
	v_and_b32_e32 v241, 0xffff0000, v123
	v_pk_mul_f32 v[242:243], v[8:9], v[234:235]
	v_pk_fma_f32 v[242:243], v[16:17], v[236:237], v[242:243]
	v_pk_fma_f32 v[242:243], v[24:25], v[238:239], v[242:243]
	v_pk_mul_f32 v[216:217], v[242:243], v[240:241]
	v_pk_fma_f32 v[244:245], v[216:217], v[216:217], v[244:245]
	v_add_f32_e32 v50, v244, v245
	s_waitcnt vmcnt(4)
	s_add_i32 s10, s24, 0x3000
	s_and_b32 s11, s10, 0xfff
	s_cmp_lg_u32 s11, 0
	s_cbranch_scc1 .Lc8_k1_6
	v_mov_b32_e32 v144, 0
	v_mov_b32_e32 v145, 0
	v_mov_b32_e32 v146, 0
	v_mov_b32_e32 v147, 0
.Lc8_k1_6:
	s_cmp_gt_u32 s11, 1
	s_cbranch_scc1 .Lc8_k2_6
	v_mov_b32_e32 v148, 0
	v_mov_b32_e32 v149, 0
	v_mov_b32_e32 v150, 0
	v_mov_b32_e32 v151, 0
.Lc8_k2_6:
	v_lshlrev_b32_e32 v234, 16, v148
	v_and_b32_e32 v235, 0xffff0000, v148
	v_lshlrev_b32_e32 v236, 16, v144
	v_and_b32_e32 v237, 0xffff0000, v144
	v_lshlrev_b32_e32 v238, 16, v140
	v_and_b32_e32 v239, 0xffff0000, v140
	v_lshlrev_b32_e32 v240, 16, v136
	v_and_b32_e32 v241, 0xffff0000, v136
	v_pk_mul_f32 v[242:243], v[2:3], v[234:235]
	v_pk_fma_f32 v[242:243], v[10:11], v[236:237], v[242:243]
	v_pk_fma_f32 v[242:243], v[18:19], v[238:239], v[242:243]
	v_pk_mul_f32 v[218:219], v[242:243], v[240:241]
	v_pk_mul_f32 v[244:245], v[218:219], v[218:219]
	v_lshlrev_b32_e32 v234, 16, v149
	v_and_b32_e32 v235, 0xffff0000, v149
	v_lshlrev_b32_e32 v236, 16, v145
	v_and_b32_e32 v237, 0xffff0000, v145
	v_lshlrev_b32_e32 v238, 16, v141
	v_and_b32_e32 v239, 0xffff0000, v141
	v_lshlrev_b32_e32 v240, 16, v137
	v_and_b32_e32 v241, 0xffff0000, v137
	v_pk_mul_f32 v[242:243], v[4:5], v[234:235]
	v_pk_fma_f32 v[242:243], v[12:13], v[236:237], v[242:243]
	v_pk_fma_f32 v[242:243], v[20:21], v[238:239], v[242:243]
	v_pk_mul_f32 v[220:221], v[242:243], v[240:241]
	v_pk_fma_f32 v[244:245], v[220:221], v[220:221], v[244:245]
	v_lshlrev_b32_e32 v234, 16, v150
	v_and_b32_e32 v235, 0xffff0000, v150
	v_lshlrev_b32_e32 v236, 16, v146
	v_and_b32_e32 v237, 0xffff0000, v146
	v_lshlrev_b32_e32 v238, 16, v142
	v_and_b32_e32 v239, 0xffff0000, v142
	v_lshlrev_b32_e32 v240, 16, v138
	v_and_b32_e32 v241, 0xffff0000, v138
	v_pk_mul_f32 v[242:243], v[6:7], v[234:235]
	v_pk_fma_f32 v[242:243], v[14:15], v[236:237], v[242:243]
	v_pk_fma_f32 v[242:243], v[22:23], v[238:239], v[242:243]
	v_pk_mul_f32 v[222:223], v[242:243], v[240:241]
	v_pk_fma_f32 v[244:245], v[222:223], v[222:223], v[244:245]
	v_lshlrev_b32_e32 v234, 16, v151
	v_and_b32_e32 v235, 0xffff0000, v151
	v_lshlrev_b32_e32 v236, 16, v147
	v_and_b32_e32 v237, 0xffff0000, v147
	v_lshlrev_b32_e32 v238, 16, v143
	v_and_b32_e32 v239, 0xffff0000, v143
	v_lshlrev_b32_e32 v240, 16, v139
	v_and_b32_e32 v241, 0xffff0000, v139
	v_pk_mul_f32 v[242:243], v[8:9], v[234:235]
	v_pk_fma_f32 v[242:243], v[16:17], v[236:237], v[242:243]
	v_pk_fma_f32 v[242:243], v[24:25], v[238:239], v[242:243]
	v_pk_mul_f32 v[224:225], v[242:243], v[240:241]
	v_pk_fma_f32 v[244:245], v[224:225], v[224:225], v[244:245]
	v_add_f32_e32 v52, v244, v245
	s_waitcnt vmcnt(0)
	s_add_i32 s10, s24, 0x3800
	s_and_b32 s11, s10, 0xfff
	s_cmp_lg_u32 s11, 0
	s_cbranch_scc1 .Lc8_k1_7
	v_mov_b32_e32 v160, 0
	v_mov_b32_e32 v161, 0
	v_mov_b32_e32 v162, 0
	v_mov_b32_e32 v163, 0
.Lc8_k1_7:
	s_cmp_gt_u32 s11, 1
	s_cbranch_scc1 .Lc8_k2_7
	v_mov_b32_e32 v164, 0
	v_mov_b32_e32 v165, 0
	v_mov_b32_e32 v166, 0
	v_mov_b32_e32 v167, 0
; __device__ __forceinline__ float wave_sum(float v) {
; #pragma unroll
;     for (int o = 1; o < 64; o <<= 1) v += __shfl_xor(v, o);
;     return v;
; }
; template <int NR>
; __device__ __forceinline__ void conv_rows(const Args& a, int r0, int rstride, int lane) {
;     ...
;     for (int i = 0; i < NR; ++i) { const int row = r0 + i * rstride; float y[8]; float s = 0.f;
; #pragma unroll
;         for (int j = 0; j < 8; ++j) { const int sh = (j & 1) * 16; const unsigned ub = bq[i][j >> 1], x0 = u0[i][j >> 1], x1 = u1[i][j >> 1], x2 = u2[i][j >> 1];
;             const float B = __uint_as_float(((ub >> sh) & 0xffffu) << 16), c_0 = __uint_as_float(((x0 >> sh) & 0xffffu) << 16), c_1 = __uint_as_float(((x1 >> sh) & 0xffffu) << 16), c_2 = __uint_as_float(((x2 >> sh) & 0xffffu) << 16);
;             const float k0 = j < 4 ? w0a[j & 3] : w0b[j & 3], k1 = j < 4 ? w1a[j & 3] : w1b[j & 3], k2 = j < 4 ? w2a[j & 3] : w2b[j & 3];
;             y[j] = B * (k0 * c_2 + k1 * c_1 + k2 * c_0); s += y[j] * y[j]; }
;         s = wave_sum(s); const float rs = rsqrtf(s * (1.f / 512.f) + EPS);
.Lc8_k2_7:
	v_lshlrev_b32_e32 v234, 16, v164
	v_and_b32_e32 v235, 0xffff0000, v164
	v_lshlrev_b32_e32 v236, 16, v160
	v_and_b32_e32 v237, 0xffff0000, v160
	v_lshlrev_b32_e32 v238, 16, v156
	v_and_b32_e32 v239, 0xffff0000, v156
	v_lshlrev_b32_e32 v240, 16, v152
	v_and_b32_e32 v241, 0xffff0000, v152
	v_pk_mul_f32 v[242:243], v[2:3], v[234:235]
	v_pk_fma_f32 v[242:243], v[10:11], v[236:237], v[242:243]
	v_pk_fma_f32 v[242:243], v[18:19], v[238:239], v[242:243]
	v_pk_mul_f32 v[226:227], v[242:243], v[240:241]
	v_pk_mul_f32 v[244:245], v[226:227], v[226:227]
	v_lshlrev_b32_e32 v234, 16, v165
	v_and_b32_e32 v235, 0xffff0000, v165
	v_lshlrev_b32_e32 v236, 16, v161
	v_and_b32_e32 v237, 0xffff0000, v161
	v_lshlrev_b32_e32 v238, 16, v157
	v_and_b32_e32 v239, 0xffff0000, v157
	v_lshlrev_b32_e32 v240, 16, v153
	v_and_b32_e32 v241, 0xffff0000, v153
	v_pk_mul_f32 v[242:243], v[4:5], v[234:235]
	v_pk_fma_f32 v[242:243], v[12:13], v[236:237], v[242:243]
	v_pk_fma_f32 v[242:243], v[20:21], v[238:239], v[242:243]
	v_pk_mul_f32 v[228:229], v[242:243], v[240:241]
	v_pk_fma_f32 v[244:245], v[228:229], v[228:229], v[244:245]
	v_lshlrev_b32_e32 v234, 16, v166
	v_and_b32_e32 v235, 0xffff0000, v166
	v_lshlrev_b32_e32 v236, 16, v162
	v_and_b32_e32 v237, 0xffff0000, v162
	v_lshlrev_b32_e32 v238, 16, v158
	v_and_b32_e32 v239, 0xffff0000, v158
	v_lshlrev_b32_e32 v240, 16, v154
	v_and_b32_e32 v241, 0xffff0000, v154
	v_pk_mul_f32 v[242:243], v[6:7], v[234:235]
	v_pk_fma_f32 v[242:243], v[14:15], v[236:237], v[242:243]
	v_pk_fma_f32 v[242:243], v[22:23], v[238:239], v[242:243]
	v_pk_mul_f32 v[230:231], v[242:243], v[240:241]
	v_pk_fma_f32 v[244:245], v[230:231], v[230:231], v[244:245]
	v_lshlrev_b32_e32 v234, 16, v167
	v_and_b32_e32 v235, 0xffff0000, v167
	v_lshlrev_b32_e32 v236, 16, v163
	v_and_b32_e32 v237, 0xffff0000, v163
	v_lshlrev_b32_e32 v238, 16, v159
	v_and_b32_e32 v239, 0xffff0000, v159
	v_lshlrev_b32_e32 v240, 16, v155
	v_and_b32_e32 v241, 0xffff0000, v155
	v_pk_mul_f32 v[242:243], v[8:9], v[234:235]
	v_pk_fma_f32 v[242:243], v[16:17], v[236:237], v[242:243]
	v_pk_fma_f32 v[242:243], v[24:25], v[238:239], v[242:243]
	v_pk_mul_f32 v[232:233], v[242:243], v[240:241]
	v_pk_fma_f32 v[244:245], v[232:233], v[232:233], v[244:245]
	v_add_f32_e32 v54, v244, v245
	v_xor_b32_e32 v56, 32, v208
	v_lshlrev_b32_e32 v56, 2, v56
	v_xor_b32_e32 v57, 16, v208
	v_lshlrev_b32_e32 v57, 2, v57
	v_xor_b32_e32 v58, 8, v208
	v_lshlrev_b32_e32 v58, 2, v58
	v_xor_b32_e32 v59, 4, v208
	v_lshlrev_b32_e32 v59, 2, v59
	v_xor_b32_e32 v60, 2, v208
	v_lshlrev_b32_e32 v60, 2, v60
	v_xor_b32_e32 v61, 1, v208
	v_lshlrev_b32_e32 v61, 2, v61
	v_mov_b32_e32 v62, 0x358637bd
	ds_bpermute_b32 v64, v56, v40
	ds_bpermute_b32 v66, v56, v42
	ds_bpermute_b32 v68, v56, v44
	ds_bpermute_b32 v70, v56, v46
	ds_bpermute_b32 v72, v56, v48
	ds_bpermute_b32 v74, v56, v50
	ds_bpermute_b32 v76, v56, v52
	ds_bpermute_b32 v78, v56, v54
	s_waitcnt lgkmcnt(0)
	v_add_f32_e32 v40, v40, v64
	v_add_f32_e32 v42, v42, v66
	v_add_f32_e32 v44, v44, v68
	v_add_f32_e32 v46, v46, v70
	v_add_f32_e32 v48, v48, v72
	v_add_f32_e32 v50, v50, v74
	v_add_f32_e32 v52, v52, v76
	v_add_f32_e32 v54, v54, v78
	ds_bpermute_b32 v64, v57, v40
	ds_bpermute_b32 v66, v57, v42
	ds_bpermute_b32 v68, v57, v44
	ds_bpermute_b32 v70, v57, v46
	ds_bpermute_b32 v72, v57, v48
	ds_bpermute_b32 v74, v57, v50
	ds_bpermute_b32 v76, v57, v52
	ds_bpermute_b32 v78, v57, v54
	s_waitcnt lgkmcnt(0)
	v_add_f32_e32 v40, v40, v64
	v_add_f32_e32 v42, v42, v66
	v_add_f32_e32 v44, v44, v68
	v_add_f32_e32 v46, v46, v70
	v_add_f32_e32 v48, v48, v72
	v_add_f32_e32 v50, v50, v74
	v_add_f32_e32 v52, v52, v76
	v_add_f32_e32 v54, v54, v78
	ds_bpermute_b32 v64, v58, v40
	ds_bpermute_b32 v66, v58, v42
	ds_bpermute_b32 v68, v58, v44
	ds_bpermute_b32 v70, v58, v46
	ds_bpermute_b32 v72, v58, v48
	ds_bpermute_b32 v74, v58, v50
	ds_bpermute_b32 v76, v58, v52
	ds_bpermute_b32 v78, v58, v54
	s_waitcnt lgkmcnt(0)
	v_add_f32_e32 v40, v40, v64
	v_add_f32_e32 v42, v42, v66
	v_add_f32_e32 v44, v44, v68
	v_add_f32_e32 v46, v46, v70
	v_add_f32_e32 v48, v48, v72
	v_add_f32_e32 v50, v50, v74
	v_add_f32_e32 v52, v52, v76
	v_add_f32_e32 v54, v54, v78
	ds_bpermute_b32 v64, v59, v40
	ds_bpermute_b32 v66, v59, v42
	ds_bpermute_b32 v68, v59, v44
	ds_bpermute_b32 v70, v59, v46
	ds_bpermute_b32 v72, v59, v48
	ds_bpermute_b32 v74, v59, v50
	ds_bpermute_b32 v76, v59, v52
	ds_bpermute_b32 v78, v59, v54
	s_waitcnt lgkmcnt(0)
	v_add_f32_e32 v40, v40, v64
	v_add_f32_e32 v42, v42, v66
	v_add_f32_e32 v44, v44, v68
	v_add_f32_e32 v46, v46, v70
	v_add_f32_e32 v48, v48, v72
	v_add_f32_e32 v50, v50, v74
	v_add_f32_e32 v52, v52, v76
	v_add_f32_e32 v54, v54, v78
	ds_bpermute_b32 v64, v60, v40
	ds_bpermute_b32 v66, v60, v42
	ds_bpermute_b32 v68, v60, v44
	ds_bpermute_b32 v70, v60, v46
	ds_bpermute_b32 v72, v60, v48
	ds_bpermute_b32 v74, v60, v50
	ds_bpermute_b32 v76, v60, v52
	ds_bpermute_b32 v78, v60, v54
	s_waitcnt lgkmcnt(0)
	v_add_f32_e32 v40, v40, v64
	v_add_f32_e32 v42, v42, v66
	v_add_f32_e32 v44, v44, v68
	v_add_f32_e32 v46, v46, v70
	v_add_f32_e32 v48, v48, v72
	v_add_f32_e32 v50, v50, v74
	v_add_f32_e32 v52, v52, v76
	v_add_f32_e32 v54, v54, v78
	ds_bpermute_b32 v64, v61, v40
	ds_bpermute_b32 v66, v61, v42
	ds_bpermute_b32 v68, v61, v44
	ds_bpermute_b32 v70, v61, v46
	ds_bpermute_b32 v72, v61, v48
	ds_bpermute_b32 v74, v61, v50
	ds_bpermute_b32 v76, v61, v52
	ds_bpermute_b32 v78, v61, v54
	s_waitcnt lgkmcnt(0)
; __device__ __forceinline__ unsigned pk2(float lo, float hi) { return pg8::cvt_pk_bf16(lo, hi); }
; template <int NR>
; __device__ __forceinline__ void conv_rows(const Args& a, int r0, int rstride, int lane) {
;     ...
;         s = wave_sum(s); const float rs = rsqrtf(s * (1.f / 512.f) + EPS);
;         v4u o; o.x = pk2(y[0] * rs * ga[0], y[1] * rs * ga[1]); o.y = pk2(y[2] * rs * ga[2], y[3] * rs * ga[3]); o.z = pk2(y[4] * rs * gb[0], y[5] * rs * gb[1]); o.w = pk2(y[6] * rs * gb[2], y[7] * rs * gb[3]);
;         pg8::st_wt16((bf16*)(ws + WS_MIX) + (size_t)row * 1024 + 512 + c0, o); }
	v_add_f32_e32 v40, v40, v64
	v_add_f32_e32 v42, v42, v66
	v_add_f32_e32 v44, v44, v68
	v_add_f32_e32 v46, v46, v70
	v_add_f32_e32 v48, v48, v72
	v_add_f32_e32 v50, v50, v74
	v_add_f32_e32 v52, v52, v76
	v_add_f32_e32 v54, v54, v78
	v_fmamk_f32 v40, v40, 0x3b000000, v62
	v_fmamk_f32 v42, v42, 0x3b000000, v62
	v_fmamk_f32 v44, v44, 0x3b000000, v62
	v_fmamk_f32 v46, v46, 0x3b000000, v62
	v_fmamk_f32 v48, v48, 0x3b000000, v62
	v_fmamk_f32 v50, v50, 0x3b000000, v62
	v_fmamk_f32 v52, v52, 0x3b000000, v62
	v_fmamk_f32 v54, v54, 0x3b000000, v62
	v_rsq_f32_e32 v40, v40
	v_rsq_f32_e32 v42, v42
	v_rsq_f32_e32 v44, v44
	v_rsq_f32_e32 v46, v46
	v_rsq_f32_e32 v48, v48
	v_rsq_f32_e32 v50, v50
	v_rsq_f32_e32 v52, v52
	v_rsq_f32_e32 v54, v54
	s_nop 1
	s_add_u32 s20, s18, 0xe000000
	s_addc_u32 s21, s19, 0
	v_pk_mul_f32 v[234:235], v[168:169], v[40:41] op_sel_hi:[1,0]
	v_pk_mul_f32 v[236:237], v[170:171], v[40:41] op_sel_hi:[1,0]
	v_pk_mul_f32 v[238:239], v[172:173], v[40:41] op_sel_hi:[1,0]
	v_pk_mul_f32 v[240:241], v[174:175], v[40:41] op_sel_hi:[1,0]
	v_pk_mul_f32 v[234:235], v[26:27], v[234:235]
	v_pk_mul_f32 v[236:237], v[28:29], v[236:237]
	v_pk_mul_f32 v[238:239], v[30:31], v[238:239]
	v_pk_mul_f32 v[240:241], v[32:33], v[240:241]
	v_cvt_pk_bf16_f32 v88, v234, v235
	v_cvt_pk_bf16_f32 v89, v236, v237
	v_cvt_pk_bf16_f32 v90, v238, v239
	v_cvt_pk_bf16_f32 v91, v240, v241
	s_add_i32 s10, s24, 0x0
	s_lshl_b32 s11, s10, 11
	s_add_u32 s4, s20, s11
	s_addc_u32 s5, s21, 0
	global_store_dwordx4 v0, v[88:91], s[4:5] offset:1024
	v_pk_mul_f32 v[234:235], v[176:177], v[42:43] op_sel_hi:[1,0]
	v_pk_mul_f32 v[236:237], v[178:179], v[42:43] op_sel_hi:[1,0]
	v_pk_mul_f32 v[238:239], v[180:181], v[42:43] op_sel_hi:[1,0]
	v_pk_mul_f32 v[240:241], v[182:183], v[42:43] op_sel_hi:[1,0]
	v_pk_mul_f32 v[234:235], v[26:27], v[234:235]
	v_pk_mul_f32 v[236:237], v[28:29], v[236:237]
	v_pk_mul_f32 v[238:239], v[30:31], v[238:239]
	v_pk_mul_f32 v[240:241], v[32:33], v[240:241]
	v_cvt_pk_bf16_f32 v92, v234, v235
	v_cvt_pk_bf16_f32 v93, v236, v237
	v_cvt_pk_bf16_f32 v94, v238, v239
	v_cvt_pk_bf16_f32 v95, v240, v241
	s_add_i32 s10, s24, 0x800
	s_lshl_b32 s11, s10, 11
	s_add_u32 s4, s20, s11
	s_addc_u32 s5, s21, 0
	global_store_dwordx4 v0, v[92:95], s[4:5] offset:1024
	v_pk_mul_f32 v[234:235], v[184:185], v[44:45] op_sel_hi:[1,0]
	v_pk_mul_f32 v[236:237], v[186:187], v[44:45] op_sel_hi:[1,0]
	v_pk_mul_f32 v[238:239], v[188:189], v[44:45] op_sel_hi:[1,0]
	v_pk_mul_f32 v[240:241], v[190:191], v[44:45] op_sel_hi:[1,0]
	v_pk_mul_f32 v[234:235], v[26:27], v[234:235]
	v_pk_mul_f32 v[236:237], v[28:29], v[236:237]
	v_pk_mul_f32 v[238:239], v[30:31], v[238:239]
	v_pk_mul_f32 v[240:241], v[32:33], v[240:241]
	v_cvt_pk_bf16_f32 v96, v234, v235
	v_cvt_pk_bf16_f32 v97, v236, v237
	v_cvt_pk_bf16_f32 v98, v238, v239
	v_cvt_pk_bf16_f32 v99, v240, v241
	s_add_i32 s10, s24, 0x1000
	s_lshl_b32 s11, s10, 11
	s_add_u32 s4, s20, s11
	s_addc_u32 s5, s21, 0
	global_store_dwordx4 v0, v[96:99], s[4:5] offset:1024
	v_pk_mul_f32 v[234:235], v[192:193], v[46:47] op_sel_hi:[1,0]
	v_pk_mul_f32 v[236:237], v[194:195], v[46:47] op_sel_hi:[1,0]
	v_pk_mul_f32 v[238:239], v[196:197], v[46:47] op_sel_hi:[1,0]
	v_pk_mul_f32 v[240:241], v[198:199], v[46:47] op_sel_hi:[1,0]
	v_pk_mul_f32 v[234:235], v[26:27], v[234:235]
	v_pk_mul_f32 v[236:237], v[28:29], v[236:237]
	v_pk_mul_f32 v[238:239], v[30:31], v[238:239]
	v_pk_mul_f32 v[240:241], v[32:33], v[240:241]
	v_cvt_pk_bf16_f32 v100, v234, v235
	v_cvt_pk_bf16_f32 v101, v236, v237
	v_cvt_pk_bf16_f32 v102, v238, v239
	v_cvt_pk_bf16_f32 v103, v240, v241
	s_add_i32 s10, s24, 0x1800
	s_lshl_b32 s11, s10, 11
	s_add_u32 s4, s20, s11
	s_addc_u32 s5, s21, 0
	global_store_dwordx4 v0, v[100:103], s[4:5] offset:1024
	v_pk_mul_f32 v[234:235], v[200:201], v[48:49] op_sel_hi:[1,0]
	v_pk_mul_f32 v[236:237], v[202:203], v[48:49] op_sel_hi:[1,0]
	v_pk_mul_f32 v[238:239], v[204:205], v[48:49] op_sel_hi:[1,0]
	v_pk_mul_f32 v[240:241], v[206:207], v[48:49] op_sel_hi:[1,0]
	v_pk_mul_f32 v[234:235], v[26:27], v[234:235]
	v_pk_mul_f32 v[236:237], v[28:29], v[236:237]
	v_pk_mul_f32 v[238:239], v[30:31], v[238:239]
	v_pk_mul_f32 v[240:241], v[32:33], v[240:241]
	v_cvt_pk_bf16_f32 v104, v234, v235
	v_cvt_pk_bf16_f32 v105, v236, v237
	v_cvt_pk_bf16_f32 v106, v238, v239
	v_cvt_pk_bf16_f32 v107, v240, v241
	s_add_i32 s10, s24, 0x2000
	s_lshl_b32 s11, s10, 11
	s_add_u32 s4, s20, s11
	s_addc_u32 s5, s21, 0
	global_store_dwordx4 v0, v[104:107], s[4:5] offset:1024
	v_pk_mul_f32 v[234:235], v[210:211], v[50:51] op_sel_hi:[1,0]
	v_pk_mul_f32 v[236:237], v[212:213], v[50:51] op_sel_hi:[1,0]
	v_pk_mul_f32 v[238:239], v[214:215], v[50:51] op_sel_hi:[1,0]
	v_pk_mul_f32 v[240:241], v[216:217], v[50:51] op_sel_hi:[1,0]
	v_pk_mul_f32 v[234:235], v[26:27], v[234:235]
	v_pk_mul_f32 v[236:237], v[28:29], v[236:237]
	v_pk_mul_f32 v[238:239], v[30:31], v[238:239]
	v_pk_mul_f32 v[240:241], v[32:33], v[240:241]
	v_cvt_pk_bf16_f32 v108, v234, v235
	v_cvt_pk_bf16_f32 v109, v236, v237
	v_cvt_pk_bf16_f32 v110, v238, v239
	v_cvt_pk_bf16_f32 v111, v240, v241
	s_add_i32 s10, s24, 0x2800
	s_lshl_b32 s11, s10, 11
	s_add_u32 s4, s20, s11
	s_addc_u32 s5, s21, 0
	global_store_dwordx4 v0, v[108:111], s[4:5] offset:1024
	v_pk_mul_f32 v[234:235], v[218:219], v[52:53] op_sel_hi:[1,0]
	v_pk_mul_f32 v[236:237], v[220:221], v[52:53] op_sel_hi:[1,0]
	v_pk_mul_f32 v[238:239], v[222:223], v[52:53] op_sel_hi:[1,0]
	v_pk_mul_f32 v[240:241], v[224:225], v[52:53] op_sel_hi:[1,0]
	v_pk_mul_f32 v[234:235], v[26:27], v[234:235]
	v_pk_mul_f32 v[236:237], v[28:29], v[236:237]
	v_pk_mul_f32 v[238:239], v[30:31], v[238:239]
	v_pk_mul_f32 v[240:241], v[32:33], v[240:241]
	v_cvt_pk_bf16_f32 v112, v234, v235
	v_cvt_pk_bf16_f32 v113, v236, v237
	v_cvt_pk_bf16_f32 v114, v238, v239
	v_cvt_pk_bf16_f32 v115, v240, v241
	s_add_i32 s10, s24, 0x3000
	s_lshl_b32 s11, s10, 11
	s_add_u32 s4, s20, s11
	s_addc_u32 s5, s21, 0
	global_store_dwordx4 v0, v[112:115], s[4:5] offset:1024
	v_pk_mul_f32 v[234:235], v[226:227], v[54:55] op_sel_hi:[1,0]
	v_pk_mul_f32 v[236:237], v[228:229], v[54:55] op_sel_hi:[1,0]
	v_pk_mul_f32 v[238:239], v[230:231], v[54:55] op_sel_hi:[1,0]
	v_pk_mul_f32 v[240:241], v[232:233], v[54:55] op_sel_hi:[1,0]
	v_pk_mul_f32 v[234:235], v[26:27], v[234:235]
	v_pk_mul_f32 v[236:237], v[28:29], v[236:237]
	v_pk_mul_f32 v[238:239], v[30:31], v[238:239]
	v_pk_mul_f32 v[240:241], v[32:33], v[240:241]
	v_cvt_pk_bf16_f32 v116, v234, v235
	v_cvt_pk_bf16_f32 v117, v236, v237
	v_cvt_pk_bf16_f32 v118, v238, v239
	v_cvt_pk_bf16_f32 v119, v240, v241
	s_add_i32 s10, s24, 0x3800
	s_lshl_b32 s11, s10, 11
	s_add_u32 s4, s20, s11
	s_addc_u32 s5, s21, 0
	global_store_dwordx4 v0, v[116:119], s[4:5] offset:1024
	s_branch .LBB0_939
; template <int NR>
; __device__ __forceinline__ void conv_rows(const Args& a, int r0, int rstride, int lane) {
;     unsigned char* ws = a.ws; const int c0 = 8 * lane;
;     const bf16* BCp = (const bf16*)(ws + WS_BC); const bf16* CUp = (const bf16*)(ws + WS_CU);
;     v4u bq[NR], u0[NR], u1[NR], u2[NR];
; #pragma unroll
;     for (int i = 0; i < NR; ++i) { const int row = r0 + i * rstride, t = row & (SEQ - 1);
;         bq[i] = *(const v4u*)(BCp + (size_t)row * 512 + c0); u0[i] = *(const v4u*)(CUp + (size_t)row * 512 + c0);
;         u1[i] = (v4u){0, 0, 0, 0}; u2[i] = (v4u){0, 0, 0, 0};
;         if (t >= 1) u1[i] = *(const v4u*)(CUp + (size_t)(row - 1) * 512 + c0);
;         if (t >= 2) u2[i] = *(const v4u*)(CUp + (size_t)(row - 2) * 512 + c0); }
;     const float* cw = a.in[I_CONVW] + c0; const float* gn = a.in[I_CONVN] + c0;
;     const f32x4 w0a = *(const f32x4*)(cw), w0b = *(const f32x4*)(cw + 4), w1a = *(const f32x4*)(cw + 512), w1b = *(const f32x4*)(cw + 516), w2a = *(const f32x4*)(cw + 1024), w2b = *(const f32x4*)(cw + 1028);
;     const f32x4 ga = *(const f32x4*)(gn), gb = *(const f32x4*)(gn + 4);
; __global__ void __launch_bounds__(NT, 2) hymba_fwd(Args args) {
;     ...
;     if (IN(5)) _Pragma("unroll") for (int rep = 0; rep < NREP(5); ++rep) {
;         if (M % (4 * NGW) == 0) { for (int r = gw; r < M; r += 4 * NGW) conv_rows<4>(args, r, NGW, lane); } else { for (int r = gw; r < M; r += NGW) conv_rows<1>(args, r, NGW, lane); }
.Lc8_generic:
	s_lshl_b32 s4, s3, 5
	s_abs_i32 s6, s4
	s_waitcnt vmcnt(0)
	v_cvt_f32_u32_e32 v0, s6
	s_sub_i32 s7, 0, s6
	s_load_dwordx4 s[16:19], s[0:1], 0xa8
	v_mov_b32_e32 v97, 0
	v_rcp_iflag_f32_e32 v0, v0
	v_lshlrev_b32_e32 v96, 4, v208
	s_mov_b64 s[4:5], 0xb000000
	v_mul_f32_e32 v0, 0x4f7ffffe, v0
	v_cvt_u32_f32_e32 v2, v0
	s_waitcnt lgkmcnt(0)
	v_lshl_add_u64 v[0:1], s[18:19], 0, v[96:97]
	v_lshl_add_u64 v[98:99], v[0:1], 0, s[4:5]
	v_lshlrev_b32_e32 v0, 5, v208
	v_readfirstlane_b32 s8, v2
	s_mul_i32 s7, s7, s8
	s_mul_hi_u32 s7, s8, s7
	s_add_i32 s8, s8, s7
	s_lshr_b32 s7, s8, 18
	s_mul_i32 s7, s7, s6
	s_sub_i32 s7, 0x4000, s7
	s_sub_i32 s8, s7, s6
	s_cmp_ge_u32 s7, s6
	s_cselect_b32 s7, s8, s7
	s_sub_i32 s8, s7, s6
	s_cmp_ge_u32 s7, s6
	s_cselect_b32 s8, s8, s7
	s_cmpk_lt_i32 s24, 0x4000
	s_cselect_b64 s[6:7], -1, 0
	s_cmp_eq_u32 s8, 0
	s_load_dwordx4 s[12:15], s[0:1], 0x40
	s_load_dwordx2 s[8:9], s[0:1], 0x50
	v_mov_b32_e32 v1, v97
	s_mov_b64 s[4:5], 0x1000
	s_waitcnt lgkmcnt(0)
	v_lshl_add_u64 v[100:101], s[14:15], 0, v[0:1]
	v_lshl_add_u64 v[102:103], s[8:9], 0, v[0:1]
	v_cndmask_b32_e64 v0, 0, 1, s[6:7]
	v_lshl_add_u64 v[104:105], v[100:101], 0, s[4:5]
	v_cmp_ne_u32_e64 s[4:5], 1, v0
	s_cbranch_scc1 .LBB0_754
	s_and_b64 vcc, exec, s[4:5]
	s_cbranch_vccnz .LBB0_753
	v_mbcnt_lo_u32_b32 v0, -1, 0
	v_mbcnt_hi_u32_b32 v0, -1, v0
	v_and_b32_e32 v2, 64, v0
	v_xor_b32_e32 v1, 32, v0
	v_add_u32_e32 v2, 64, v2
	v_cmp_lt_i32_e32 vcc, v1, v2
	s_ashr_i32 s25, s24, 31
	s_lshl_b64 s[6:7], s[24:25], 11
	v_cndmask_b32_e32 v1, v0, v1, vcc
	v_lshlrev_b32_e32 v12, 2, v1
	v_xor_b32_e32 v1, 16, v0
	v_cmp_lt_i32_e32 vcc, v1, v2
	s_add_u32 s6, s18, s6
	v_mov_b32_e32 v97, 0
	v_cndmask_b32_e32 v1, v0, v1, vcc
	v_lshlrev_b32_e32 v13, 2, v1
	v_xor_b32_e32 v1, 8, v0
	v_cmp_lt_i32_e32 vcc, v1, v2
	s_addc_u32 s7, s19, s7
	s_ashr_i32 s59, s58, 31
	v_cndmask_b32_e32 v1, v0, v1, vcc
	v_lshlrev_b32_e32 v14, 2, v1
	v_xor_b32_e32 v1, 4, v0
	v_cmp_lt_i32_e32 vcc, v1, v2
	s_lshl_b64 s[8:9], s[24:25], 10
	v_mov_b32_e32 v18, 0x358637bd
	v_cndmask_b32_e32 v1, v0, v1, vcc
	v_lshlrev_b32_e32 v15, 2, v1
	v_xor_b32_e32 v1, 2, v0
	v_cmp_lt_i32_e32 vcc, v1, v2
	s_mov_b32 s10, 0x800000
	s_mov_b32 s11, s24
	v_cndmask_b32_e32 v1, v0, v1, vcc
	v_lshlrev_b32_e32 v16, 2, v1
	v_xor_b32_e32 v1, 1, v0
	v_cmp_lt_i32_e32 vcc, v1, v2
	s_nop 1
	v_cndmask_b32_e32 v0, v0, v1, vcc
	v_lshlrev_b32_e32 v17, 2, v0
	v_lshl_add_u64 v[0:1], s[6:7], 0, v[96:97]
	s_mov_b64 s[6:7], 0xe000400
	v_lshl_add_u64 v[8:9], v[0:1], 0, s[6:7]
	s_lshl_b64 s[6:7], s[58:59], 11
	s_add_u32 s8, s18, s8
	s_addc_u32 s9, s19, s9
	v_lshl_add_u64 v[0:1], s[8:9], 0, v[96:97]
	s_mov_b64 s[8:9], 0xa000000
	v_lshl_add_u64 v[10:11], v[0:1], 0, s[8:9]
	s_lshl_b64 s[8:9], s[58:59], 10
	s_branch .LBB0_748
